# v26 + grid barrier: first-arriving workgroup of each XCD pre-flushes the L2 (buffer_wbl2) before polling
# speedup vs baseline: 1.0497x; 1.0497x over previous
; __device__ __forceinline__ unsigned xb_ld(unsigned* p)              { return __hip_atomic_load(p, __ATOMIC_RELAXED, __HIP_MEMORY_SCOPE_AGENT); }
; __device__ __forceinline__ unsigned xb_add(unsigned* p, unsigned v) { return __hip_atomic_fetch_add(p, v, __ATOMIC_RELAXED, __HIP_MEMORY_SCOPE_AGENT); }
; #define XB_SPIN(cond, bar) do { unsigned _sp = 0; while (cond) { __builtin_amdgcn_s_sleep(1); \
;     if ((++_sp & 255u) == 0u) { if (xb_ld(&(bar)[XB_TMO])) break; if (_sp > XB_SPIN_CAP) { atomicAdd(&(bar)[XB_TMO], 1u); break; } } } } while (0)
; __device__ __forceinline__ void xcd_barrier(const XcdBarrier& b) {
;     ...
;         const unsigned old = xb_add(&bar[XB_XSUB(b.x)], 1u);
;         const unsigned gen = old / nloc;
;         if (old + 1u == (gen + 1u) * nloc) {
;             __builtin_amdgcn_fence(__ATOMIC_RELEASE, "agent");
;             asm volatile("s_waitcnt vmcnt(0)" ::: "memory");
;             asm volatile("buffer_inv sc1" ::: "memory");
;             const unsigned og = xb_add(&bar[XB_TOP], 1u);
;             const unsigned tg = og / nx;
;             const bool last_top = (og + 1u == (tg + 1u) * nx);
;             if (last_top) (void)__hip_atomic_fetch_add(&bar[XB_TOPGEN], 1u, __ATOMIC_RELAXED, __HIP_MEMORY_SCOPE_AGENT);
;             asm volatile("s_waitcnt vmcnt(0)" ::: "memory");
;             (void)__hip_atomic_fetch_add(&bar[XB_XGEN(b.x)], 1u, __ATOMIC_RELAXED, __HIP_MEMORY_SCOPE_AGENT);
;             if (!last_top) XB_SPIN(xb_ld(&bar[XB_TOPGEN]) == tg, bar);
;         } else {
;             asm volatile("buffer_inv sc1" ::: "memory");
;             { unsigned _sp = 0; for (;;) { const unsigned a_ = xb_ld(&bar[XB_TOPGEN]), c_ = xb_ld(&bar[XB_XGEN(b.x)]); if (a_ != gen && c_ != gen) break; __builtin_amdgcn_s_sleep(1);
;                 if ((++_sp & 255u) == 0u) { if (xb_ld(&bar[XB_TMO])) break; if (_sp > XB_SPIN_CAP) { atomicAdd(&bar[XB_TMO], 1u); break; } } } }
.LBB0_90:
	s_or_b64 exec, exec, s[10:11]
	v_cvt_f32_u32_e32 v5, v3
	s_waitcnt vmcnt(0)
	v_readfirstlane_b32 s0, v4
	v_sub_u32_e32 v4, 0, v3
	v_rcp_iflag_f32_e32 v5, v5
	v_add_u32_e32 v6, s0, v2
	v_mul_f32_e32 v5, 0x4f7ffffe, v5
	v_cvt_u32_f32_e32 v5, v5
	v_mul_lo_u32 v2, v4, v5
	v_mul_hi_u32 v2, v5, v2
	v_add_u32_e32 v2, v5, v2
	v_mul_hi_u32 v2, v6, v2
	v_mul_lo_u32 v4, v2, v3
	v_sub_u32_e32 v4, v6, v4
	v_add_u32_e32 v5, 1, v2
	v_cmp_ge_u32_e32 vcc, v4, v3
	s_nop 1
	v_cndmask_b32_e32 v2, v2, v5, vcc
	v_sub_u32_e32 v5, v4, v3
	v_cndmask_b32_e32 v4, v4, v5, vcc
	v_add_u32_e32 v5, 1, v2
	v_cmp_ge_u32_e32 vcc, v4, v3
	v_add_u32_e32 v4, 1, v6
	s_nop 0
	v_cndmask_b32_e32 v2, v2, v5, vcc
	v_mul_lo_u32 v5, v3, v2
	v_add_u32_e32 v3, v5, v3
	v_cmp_ne_u32_e32 vcc, v4, v3
	s_and_saveexec_b64 s[0:1], vcc
	s_xor_b64 s[10:11], exec, s[0:1]
	s_cbranch_execz .LBB0_104
	v_cmp_eq_u32_e32 vcc, v5, v6
	s_cbranch_vccz .Lpf_skip_0
	buffer_wbl2 sc1
	s_waitcnt vmcnt(0)
.Lpf_skip_0:
	buffer_inv sc1
	s_waitcnt lgkmcnt(0)
	v_mov_b32_e32 v1, 0x7000
	v_mov_b32_e32 v3, 0x2000
	global_load_dword v1, v1, s[50:51] offset:1280 sc1
	s_add_u32 s16, s50, 0x7500
	global_load_dword v3, v3, s[8:9] offset:1024 sc1
	s_addc_u32 s17, s51, 0
	s_add_u32 s18, s8, 0x2400
	s_addc_u32 s19, s9, 0
	s_waitcnt vmcnt(1)
	v_cmp_eq_u32_e32 vcc, v1, v2
	s_waitcnt vmcnt(0)
	v_cmp_eq_u32_e64 s[0:1], v3, v2
	s_or_b64 s[0:1], vcc, s[0:1]
	s_and_saveexec_b64 s[12:13], s[0:1]
	s_cbranch_execz .LBB0_103
	s_add_u32 s14, s50, 0x4200
	s_addc_u32 s15, s51, 0
	s_mov_b32 s3, 1
	s_mov_b64 s[20:21], 0
	v_mov_b32_e32 v1, 0
	s_branch .LBB0_94

; __device__ __forceinline__ unsigned xb_ld(unsigned* p)              { return __hip_atomic_load(p, __ATOMIC_RELAXED, __HIP_MEMORY_SCOPE_AGENT); }
; __device__ __forceinline__ unsigned xb_add(unsigned* p, unsigned v) { return __hip_atomic_fetch_add(p, v, __ATOMIC_RELAXED, __HIP_MEMORY_SCOPE_AGENT); }
; #define XB_SPIN(cond, bar) do { unsigned _sp = 0; while (cond) { __builtin_amdgcn_s_sleep(1); \
;     if ((++_sp & 255u) == 0u) { if (xb_ld(&(bar)[XB_TMO])) break; if (_sp > XB_SPIN_CAP) { atomicAdd(&(bar)[XB_TMO], 1u); break; } } } } while (0)
; __device__ __forceinline__ void xcd_barrier(const XcdBarrier& b) {
;     ...
;         const unsigned old = xb_add(&bar[XB_XSUB(b.x)], 1u);
;         const unsigned gen = old / nloc;
;         if (old + 1u == (gen + 1u) * nloc) {
;             __builtin_amdgcn_fence(__ATOMIC_RELEASE, "agent");
;             asm volatile("s_waitcnt vmcnt(0)" ::: "memory");
;             asm volatile("buffer_inv sc1" ::: "memory");
;             const unsigned og = xb_add(&bar[XB_TOP], 1u);
;             const unsigned tg = og / nx;
;             const bool last_top = (og + 1u == (tg + 1u) * nx);
;             if (last_top) (void)__hip_atomic_fetch_add(&bar[XB_TOPGEN], 1u, __ATOMIC_RELAXED, __HIP_MEMORY_SCOPE_AGENT);
;             asm volatile("s_waitcnt vmcnt(0)" ::: "memory");
;             (void)__hip_atomic_fetch_add(&bar[XB_XGEN(b.x)], 1u, __ATOMIC_RELAXED, __HIP_MEMORY_SCOPE_AGENT);
;             if (!last_top) XB_SPIN(xb_ld(&bar[XB_TOPGEN]) == tg, bar);
;         } else {
;             asm volatile("buffer_inv sc1" ::: "memory");
;             { unsigned _sp = 0; for (;;) { const unsigned a_ = xb_ld(&bar[XB_TOPGEN]), c_ = xb_ld(&bar[XB_XGEN(b.x)]); if (a_ != gen && c_ != gen) break; __builtin_amdgcn_s_sleep(1);
;                 if ((++_sp & 255u) == 0u) { if (xb_ld(&bar[XB_TMO])) break; if (_sp > XB_SPIN_CAP) { atomicAdd(&bar[XB_TMO], 1u); break; } } } }
.LBB0_237:
	s_or_b64 exec, exec, s[10:11]
	v_cvt_f32_u32_e32 v6, v4
	s_waitcnt vmcnt(0)
	v_readfirstlane_b32 s0, v5
	v_sub_u32_e32 v5, 0, v4
	v_rcp_iflag_f32_e32 v6, v6
	v_add_u32_e32 v7, s0, v3
	v_mul_f32_e32 v6, 0x4f7ffffe, v6
	v_cvt_u32_f32_e32 v6, v6
	v_mul_lo_u32 v3, v5, v6
	v_mul_hi_u32 v3, v6, v3
	v_add_u32_e32 v3, v6, v3
	v_mul_hi_u32 v3, v7, v3
	v_mul_lo_u32 v5, v3, v4
	v_sub_u32_e32 v5, v7, v5
	v_add_u32_e32 v6, 1, v3
	v_cmp_ge_u32_e32 vcc, v5, v4
	s_nop 1
	v_cndmask_b32_e32 v3, v3, v6, vcc
	v_sub_u32_e32 v6, v5, v4
	v_cndmask_b32_e32 v5, v5, v6, vcc
	v_add_u32_e32 v6, 1, v3
	v_cmp_ge_u32_e32 vcc, v5, v4
	v_add_u32_e32 v5, 1, v7
	s_nop 0
	v_cndmask_b32_e32 v3, v3, v6, vcc
	v_mul_lo_u32 v6, v4, v3
	v_add_u32_e32 v4, v6, v4
	v_cmp_ne_u32_e32 vcc, v5, v4
	s_and_saveexec_b64 s[0:1], vcc
	s_xor_b64 s[10:11], exec, s[0:1]
	s_cbranch_execz .LBB0_251
	v_cmp_eq_u32_e32 vcc, v6, v7
	s_cbranch_vccz .Lpf_skip_1
	buffer_wbl2 sc1
	s_waitcnt vmcnt(0)
.Lpf_skip_1:
	buffer_inv sc1
	s_waitcnt lgkmcnt(0)
	v_mov_b32_e32 v2, 0x7000
	v_mov_b32_e32 v4, 0x2000
	global_load_dword v2, v2, s[50:51] offset:1280 sc1
	s_add_u32 s16, s50, 0x7500
	global_load_dword v4, v4, s[8:9] offset:1024 sc1
	s_addc_u32 s17, s51, 0
	s_add_u32 s18, s8, 0x2400
	s_addc_u32 s19, s9, 0
	s_waitcnt vmcnt(1)
	v_cmp_eq_u32_e32 vcc, v2, v3
	s_waitcnt vmcnt(0)
	v_cmp_eq_u32_e64 s[0:1], v4, v3
	s_or_b64 s[0:1], vcc, s[0:1]
	s_and_saveexec_b64 s[12:13], s[0:1]
	s_cbranch_execz .LBB0_250
	s_add_u32 s14, s50, 0x4200
	s_addc_u32 s15, s51, 0
	s_mov_b32 s3, 1
	s_mov_b64 s[20:21], 0
	v_mov_b32_e32 v2, 0
	s_branch .LBB0_241

; __device__ __forceinline__ unsigned xb_ld(unsigned* p)              { return __hip_atomic_load(p, __ATOMIC_RELAXED, __HIP_MEMORY_SCOPE_AGENT); }
; __device__ __forceinline__ unsigned xb_add(unsigned* p, unsigned v) { return __hip_atomic_fetch_add(p, v, __ATOMIC_RELAXED, __HIP_MEMORY_SCOPE_AGENT); }
; #define XB_SPIN(cond, bar) do { unsigned _sp = 0; while (cond) { __builtin_amdgcn_s_sleep(1); \
;     if ((++_sp & 255u) == 0u) { if (xb_ld(&(bar)[XB_TMO])) break; if (_sp > XB_SPIN_CAP) { atomicAdd(&(bar)[XB_TMO], 1u); break; } } } } while (0)
; __device__ __forceinline__ void xcd_barrier(const XcdBarrier& b) {
;     ...
;         const unsigned old = xb_add(&bar[XB_XSUB(b.x)], 1u);
;         const unsigned gen = old / nloc;
;         if (old + 1u == (gen + 1u) * nloc) {
;             __builtin_amdgcn_fence(__ATOMIC_RELEASE, "agent");
;             asm volatile("s_waitcnt vmcnt(0)" ::: "memory");
;             asm volatile("buffer_inv sc1" ::: "memory");
;             const unsigned og = xb_add(&bar[XB_TOP], 1u);
;             const unsigned tg = og / nx;
;             const bool last_top = (og + 1u == (tg + 1u) * nx);
;             if (last_top) (void)__hip_atomic_fetch_add(&bar[XB_TOPGEN], 1u, __ATOMIC_RELAXED, __HIP_MEMORY_SCOPE_AGENT);
;             asm volatile("s_waitcnt vmcnt(0)" ::: "memory");
;             (void)__hip_atomic_fetch_add(&bar[XB_XGEN(b.x)], 1u, __ATOMIC_RELAXED, __HIP_MEMORY_SCOPE_AGENT);
;             if (!last_top) XB_SPIN(xb_ld(&bar[XB_TOPGEN]) == tg, bar);
;         } else {
;             asm volatile("buffer_inv sc1" ::: "memory");
;             { unsigned _sp = 0; for (;;) { const unsigned a_ = xb_ld(&bar[XB_TOPGEN]), c_ = xb_ld(&bar[XB_XGEN(b.x)]); if (a_ != gen && c_ != gen) break; __builtin_amdgcn_s_sleep(1);
;                 if ((++_sp & 255u) == 0u) { if (xb_ld(&bar[XB_TMO])) break; if (_sp > XB_SPIN_CAP) { atomicAdd(&bar[XB_TMO], 1u); break; } } } }
.LBB0_720:
	s_or_b64 exec, exec, s[12:13]
	v_cvt_f32_u32_e32 v6, v4
	s_waitcnt vmcnt(0)
	v_readfirstlane_b32 s0, v5
	v_sub_u32_e32 v5, 0, v4
	v_rcp_iflag_f32_e32 v6, v6
	v_add_u32_e32 v7, s0, v3
	v_mul_f32_e32 v6, 0x4f7ffffe, v6
	v_cvt_u32_f32_e32 v6, v6
	v_mul_lo_u32 v3, v5, v6
	v_mul_hi_u32 v3, v6, v3
	v_add_u32_e32 v3, v6, v3
	v_mul_hi_u32 v3, v7, v3
	v_mul_lo_u32 v5, v3, v4
	v_sub_u32_e32 v5, v7, v5
	v_add_u32_e32 v6, 1, v3
	v_cmp_ge_u32_e32 vcc, v5, v4
	s_nop 1
	v_cndmask_b32_e32 v3, v3, v6, vcc
	v_sub_u32_e32 v6, v5, v4
	v_cndmask_b32_e32 v5, v5, v6, vcc
	v_add_u32_e32 v6, 1, v3
	v_cmp_ge_u32_e32 vcc, v5, v4
	v_add_u32_e32 v5, 1, v7
	s_nop 0
	v_cndmask_b32_e32 v3, v3, v6, vcc
	v_mul_lo_u32 v6, v4, v3
	v_add_u32_e32 v4, v6, v4
	v_cmp_ne_u32_e32 vcc, v5, v4
	s_and_saveexec_b64 s[0:1], vcc
	s_xor_b64 s[12:13], exec, s[0:1]
	s_cbranch_execz .LBB0_734
	v_cmp_eq_u32_e32 vcc, v6, v7
	s_cbranch_vccz .Lpf_skip_4
	buffer_wbl2 sc1
	s_waitcnt vmcnt(0)
.Lpf_skip_4:
	buffer_inv sc1
	s_waitcnt lgkmcnt(0)
	v_mov_b32_e32 v2, 0x7000
	v_mov_b32_e32 v4, 0x2000
	global_load_dword v2, v2, s[50:51] offset:1280 sc1
	s_add_u32 s18, s50, 0x7500
	global_load_dword v4, v4, s[10:11] offset:1024 sc1
	s_addc_u32 s19, s51, 0
	s_add_u32 s20, s10, 0x2400
	s_addc_u32 s21, s11, 0
	s_waitcnt vmcnt(1)
	v_cmp_eq_u32_e32 vcc, v2, v3
	s_waitcnt vmcnt(0)
	v_cmp_eq_u32_e64 s[0:1], v4, v3
	s_or_b64 s[0:1], vcc, s[0:1]
	s_and_saveexec_b64 s[14:15], s[0:1]
	s_cbranch_execz .LBB0_733
	s_add_u32 s16, s50, 0x4200
	s_addc_u32 s17, s51, 0
	s_mov_b32 s3, 1
	s_mov_b64 s[22:23], 0
	v_mov_b32_e32 v2, 0
	s_branch .LBB0_724
